# P12 final norm: lane-to-element remap so every load/store instruction is fully contiguous (dwordx2 loads, dwordx4 stores)
# speedup vs baseline: 1.0502x; 1.0043x over previous
.LBB0_1335:
	s_cmp_lt_i32 s56, 13
	s_cselect_b64 s[2:3], -1, 0
	s_and_b64 s[0:1], s[2:3], s[0:1]
	s_cmp_lt_i32 s58, 0x8000
	s_cselect_b64 s[2:3], -1, 0
	s_and_b64 s[0:1], s[0:1], s[2:3]
	s_andn2_b64 vcc, exec, s[0:1]
	s_cbranch_vccnz .LBB0_1347
	v_readlane_b32 s0, v244, 23
	v_readlane_b32 s1, v244, 24
	v_lshlrev_b32_e32 v1, 2, v144
	v_xor_b32_e32 v40, 4, v1
	v_xor_b32_e32 v41, 8, v1
	v_xor_b32_e32 v42, 16, v1
	v_xor_b32_e32 v43, 32, v1
	v_xor_b32_e32 v44, 64, v1
	v_xor_b32_e32 v45, 0x80, v1
	v_lshlrev_b32_e32 v2, 4, v144
	v_lshlrev_b32_e32 v3, 3, v144
	v_mov_b32_e32 v86, 0x358637bd
	s_add_u32 s2, s54, 0x2400000
	s_addc_u32 s3, s55, 0
	s_mov_b32 s10, s58
	s_add_i32 s11, s10, s75
	s_cmp_lt_i32 s11, 0x8000
	s_cselect_b32 s11, s11, s10
	s_lshl_b32 s12, s10, 11
	s_lshl_b32 s13, s11, 11
	s_add_u32 s4, s2, s12
	s_addc_u32 s5, s3, 0
	s_add_u32 s6, s2, s13
	s_addc_u32 s7, s3, 0
	global_load_dwordx2 v[24:25], v3, s[4:5]
	global_load_dwordx2 v[26:27], v3, s[4:5] offset:512
	global_load_dwordx2 v[28:29], v3, s[4:5] offset:1024
	global_load_dwordx2 v[30:31], v3, s[4:5] offset:1536
	global_load_dwordx2 v[32:33], v3, s[6:7]
	global_load_dwordx2 v[34:35], v3, s[6:7] offset:512
	global_load_dwordx2 v[36:37], v3, s[6:7] offset:1024
	global_load_dwordx2 v[38:39], v3, s[6:7] offset:1536
	global_load_dwordx4 v[100:103], v2, s[0:1]
	global_load_dwordx4 v[104:107], v2, s[0:1] offset:1024
	global_load_dwordx4 v[108:111], v2, s[0:1] offset:2048
	global_load_dwordx4 v[112:115], v2, s[0:1] offset:3072
	s_waitcnt vmcnt(0)
.Lp12_loop:
	v_lshlrev_b32_e32 v48, 16, v24
	v_and_b32_e32 v49, 0xffff0000, v24
	v_lshlrev_b32_e32 v50, 16, v25
	v_and_b32_e32 v51, 0xffff0000, v25
	v_lshlrev_b32_e32 v52, 16, v26
	v_and_b32_e32 v53, 0xffff0000, v26
	v_lshlrev_b32_e32 v54, 16, v27
	v_and_b32_e32 v55, 0xffff0000, v27
	v_lshlrev_b32_e32 v56, 16, v28
	v_and_b32_e32 v57, 0xffff0000, v28
	v_lshlrev_b32_e32 v58, 16, v29
	v_and_b32_e32 v59, 0xffff0000, v29
	v_lshlrev_b32_e32 v60, 16, v30
	v_and_b32_e32 v61, 0xffff0000, v30
	v_lshlrev_b32_e32 v62, 16, v31
	v_and_b32_e32 v63, 0xffff0000, v31
	v_lshlrev_b32_e32 v64, 16, v32
	v_and_b32_e32 v65, 0xffff0000, v32
	v_lshlrev_b32_e32 v66, 16, v33
	v_and_b32_e32 v67, 0xffff0000, v33
	v_lshlrev_b32_e32 v68, 16, v34
	v_and_b32_e32 v69, 0xffff0000, v34
	v_lshlrev_b32_e32 v70, 16, v35
	v_and_b32_e32 v71, 0xffff0000, v35
	v_lshlrev_b32_e32 v72, 16, v36
	v_and_b32_e32 v73, 0xffff0000, v36
	v_lshlrev_b32_e32 v74, 16, v37
	v_and_b32_e32 v75, 0xffff0000, v37
	v_lshlrev_b32_e32 v76, 16, v38
	v_and_b32_e32 v77, 0xffff0000, v38
	v_lshlrev_b32_e32 v78, 16, v39
	v_and_b32_e32 v79, 0xffff0000, v39
	s_lshl_b32 s12, s10, 12
	s_lshl_b32 s13, s11, 12
	s_add_u32 s14, s52, s12
	s_addc_u32 s15, s53, 0
	s_add_u32 s16, s52, s13
	s_addc_u32 s17, s53, 0
	s_add_i32 s10, s10, s75
	s_add_i32 s10, s10, s75
	s_cmp_lt_i32 s10, 0x8000
	s_cselect_b32 s18, 1, 0
	s_cbranch_scc0 .Lp12_nonext
	s_add_i32 s11, s10, s75
	s_cmp_lt_i32 s11, 0x8000
	s_cselect_b32 s11, s11, s10
	s_lshl_b32 s12, s10, 11
	s_lshl_b32 s13, s11, 11
	s_add_u32 s4, s2, s12
	s_addc_u32 s5, s3, 0
	s_add_u32 s6, s2, s13
	s_addc_u32 s7, s3, 0
	global_load_dwordx2 v[24:25], v3, s[4:5]
	global_load_dwordx2 v[26:27], v3, s[4:5] offset:512
	global_load_dwordx2 v[28:29], v3, s[4:5] offset:1024
	global_load_dwordx2 v[30:31], v3, s[4:5] offset:1536
	global_load_dwordx2 v[32:33], v3, s[6:7]
	global_load_dwordx2 v[34:35], v3, s[6:7] offset:512
	global_load_dwordx2 v[36:37], v3, s[6:7] offset:1024
	global_load_dwordx2 v[38:39], v3, s[6:7] offset:1536
.Lp12_nonext:
	v_mul_f32_e32 v80, v48, v48
	v_mul_f32_e32 v82, v64, v64
	v_mul_f32_e32 v81, v49, v49
	v_mul_f32_e32 v83, v65, v65
	v_fmac_f32_e32 v80, v50, v50
	v_fmac_f32_e32 v82, v66, v66
	v_fmac_f32_e32 v81, v51, v51
	v_fmac_f32_e32 v83, v67, v67
	v_fmac_f32_e32 v80, v52, v52
	v_fmac_f32_e32 v82, v68, v68
	v_fmac_f32_e32 v81, v53, v53
	v_fmac_f32_e32 v83, v69, v69
	v_fmac_f32_e32 v80, v54, v54
	v_fmac_f32_e32 v82, v70, v70
	v_fmac_f32_e32 v81, v55, v55
	v_fmac_f32_e32 v83, v71, v71
	v_fmac_f32_e32 v80, v56, v56
	v_fmac_f32_e32 v82, v72, v72
	v_fmac_f32_e32 v81, v57, v57
	v_fmac_f32_e32 v83, v73, v73
	v_fmac_f32_e32 v80, v58, v58
	v_fmac_f32_e32 v82, v74, v74
	v_fmac_f32_e32 v81, v59, v59
	v_fmac_f32_e32 v83, v75, v75
	v_fmac_f32_e32 v80, v60, v60
	v_fmac_f32_e32 v82, v76, v76
	v_fmac_f32_e32 v81, v61, v61
	v_fmac_f32_e32 v83, v77, v77
	v_fmac_f32_e32 v80, v62, v62
	v_fmac_f32_e32 v82, v78, v78
	v_fmac_f32_e32 v81, v63, v63
	v_fmac_f32_e32 v83, v79, v79
	v_add_f32_e32 v80, v80, v81
	v_add_f32_e32 v82, v82, v83
	ds_bpermute_b32 v84, v40, v80
	ds_bpermute_b32 v85, v40, v82
	s_waitcnt lgkmcnt(1)
	v_add_f32_e32 v80, v80, v84
	s_waitcnt lgkmcnt(0)
	v_add_f32_e32 v82, v82, v85
	ds_bpermute_b32 v84, v41, v80
	ds_bpermute_b32 v85, v41, v82
	s_waitcnt lgkmcnt(1)
	v_add_f32_e32 v80, v80, v84
	s_waitcnt lgkmcnt(0)
	v_add_f32_e32 v82, v82, v85
	ds_bpermute_b32 v84, v42, v80
	ds_bpermute_b32 v85, v42, v82
	s_waitcnt lgkmcnt(1)
	v_add_f32_e32 v80, v80, v84
	s_waitcnt lgkmcnt(0)
	v_add_f32_e32 v82, v82, v85
	ds_bpermute_b32 v84, v43, v80
	ds_bpermute_b32 v85, v43, v82
	s_waitcnt lgkmcnt(1)
	v_add_f32_e32 v80, v80, v84
	s_waitcnt lgkmcnt(0)
	v_add_f32_e32 v82, v82, v85
	ds_bpermute_b32 v84, v44, v80
	ds_bpermute_b32 v85, v44, v82
	s_waitcnt lgkmcnt(1)
	v_add_f32_e32 v80, v80, v84
	s_waitcnt lgkmcnt(0)
	v_add_f32_e32 v82, v82, v85
	ds_bpermute_b32 v84, v45, v80
	ds_bpermute_b32 v85, v45, v82
	s_waitcnt lgkmcnt(1)
	v_add_f32_e32 v80, v80, v84
	s_waitcnt lgkmcnt(0)
	v_add_f32_e32 v82, v82, v85
	v_fmamk_f32 v80, v80, 0x3a800000, v86
	v_fmamk_f32 v82, v82, 0x3a800000, v86
	v_rsq_f32_e32 v80, v80
	v_rsq_f32_e32 v82, v82
	s_nop 0
	v_mul_f32_e32 v48, v48, v80
	v_mul_f32_e32 v64, v64, v82
	v_mul_f32_e32 v49, v49, v80
	v_mul_f32_e32 v65, v65, v82
	v_mul_f32_e32 v50, v50, v80
	v_mul_f32_e32 v66, v66, v82
	v_mul_f32_e32 v51, v51, v80
	v_mul_f32_e32 v67, v67, v82
	v_mul_f32_e32 v52, v52, v80
	v_mul_f32_e32 v68, v68, v82
	v_mul_f32_e32 v53, v53, v80
	v_mul_f32_e32 v69, v69, v82
	v_mul_f32_e32 v54, v54, v80
	v_mul_f32_e32 v70, v70, v82
	v_mul_f32_e32 v55, v55, v80
	v_mul_f32_e32 v71, v71, v82
	v_mul_f32_e32 v56, v56, v80
	v_mul_f32_e32 v72, v72, v82
	v_mul_f32_e32 v57, v57, v80
	v_mul_f32_e32 v73, v73, v82
	v_mul_f32_e32 v58, v58, v80
	v_mul_f32_e32 v74, v74, v82
	v_mul_f32_e32 v59, v59, v80
	v_mul_f32_e32 v75, v75, v82
	v_mul_f32_e32 v60, v60, v80
	v_mul_f32_e32 v76, v76, v82
	v_mul_f32_e32 v61, v61, v80
	v_mul_f32_e32 v77, v77, v82
	v_mul_f32_e32 v62, v62, v80
	v_mul_f32_e32 v78, v78, v82
	v_mul_f32_e32 v63, v63, v80
	v_mul_f32_e32 v79, v79, v82
	v_mul_f32_e32 v48, v48, v100
	v_mul_f32_e32 v64, v64, v100
	v_mul_f32_e32 v49, v49, v101
	v_mul_f32_e32 v65, v65, v101
	v_mul_f32_e32 v50, v50, v102
	v_mul_f32_e32 v66, v66, v102
	v_mul_f32_e32 v51, v51, v103
	v_mul_f32_e32 v67, v67, v103
	v_mul_f32_e32 v52, v52, v104
	v_mul_f32_e32 v68, v68, v104
	v_mul_f32_e32 v53, v53, v105
	v_mul_f32_e32 v69, v69, v105
	v_mul_f32_e32 v54, v54, v106
	v_mul_f32_e32 v70, v70, v106
	v_mul_f32_e32 v55, v55, v107
	v_mul_f32_e32 v71, v71, v107
	v_mul_f32_e32 v56, v56, v108
	v_mul_f32_e32 v72, v72, v108
	v_mul_f32_e32 v57, v57, v109
	v_mul_f32_e32 v73, v73, v109
	v_mul_f32_e32 v58, v58, v110
	v_mul_f32_e32 v74, v74, v110
	v_mul_f32_e32 v59, v59, v111
	v_mul_f32_e32 v75, v75, v111
	v_mul_f32_e32 v60, v60, v112
	v_mul_f32_e32 v76, v76, v112
	v_mul_f32_e32 v61, v61, v113
	v_mul_f32_e32 v77, v77, v113
	v_mul_f32_e32 v62, v62, v114
	v_mul_f32_e32 v78, v78, v114
	v_mul_f32_e32 v63, v63, v115
	v_mul_f32_e32 v79, v79, v115
	global_store_dwordx4 v2, v[48:51], s[14:15]
	global_store_dwordx4 v2, v[52:55], s[14:15] offset:1024
	global_store_dwordx4 v2, v[56:59], s[14:15] offset:2048
	global_store_dwordx4 v2, v[60:63], s[14:15] offset:3072
	global_store_dwordx4 v2, v[64:67], s[16:17]
	global_store_dwordx4 v2, v[68:71], s[16:17] offset:1024
	global_store_dwordx4 v2, v[72:75], s[16:17] offset:2048
	global_store_dwordx4 v2, v[76:79], s[16:17] offset:3072
	s_cmp_lg_u32 s18, 0
	s_cbranch_scc0 .LBB0_1347
	s_waitcnt vmcnt(8)
	s_branch .Lp12_loop
